# v74 + first grid barrier census: 16 serialized counter loads issued as one batch
# baseline (speedup 1.0000x reference)
.LBB0_80:
	v_readlane_b32 s4, v233, 55
	v_readlane_b32 s5, v233, 56
	s_mov_b64 s[12:13], -1
	s_waitcnt lgkmcnt(0)
	s_nop 4
	global_load_dword v0, v16, s[4:5] sc1
	global_load_dword v1, v16, s[4:5] offset:256 sc1
	global_load_dword v2, v16, s[4:5] offset:512 sc1
	global_load_dword v3, v16, s[4:5] offset:768 sc1
	global_load_dword v4, v16, s[4:5] offset:1024 sc1
	global_load_dword v5, v16, s[4:5] offset:1280 sc1
	global_load_dword v6, v16, s[4:5] offset:1536 sc1
	global_load_dword v7, v16, s[4:5] offset:1792 sc1
	global_load_dword v8, v16, s[4:5] offset:2048 sc1
	global_load_dword v9, v16, s[4:5] offset:2304 sc1
	global_load_dword v10, v16, s[4:5] offset:2560 sc1
	global_load_dword v11, v16, s[4:5] offset:2816 sc1
	global_load_dword v12, v16, s[4:5] offset:3072 sc1
	global_load_dword v13, v16, s[4:5] offset:3328 sc1
	global_load_dword v14, v16, s[4:5] offset:3584 sc1
	global_load_dword v15, v16, s[4:5] offset:3840 sc1
	s_waitcnt vmcnt(0)
	v_add_u32_e32 v17, v1, v0
	v_add_u32_e32 v17, v17, v2
	v_add_u32_e32 v17, v17, v3
	v_add_u32_e32 v17, v17, v4
	v_add_u32_e32 v17, v17, v5
	v_add_u32_e32 v17, v17, v6
	v_add_u32_e32 v17, v17, v7
	v_add_u32_e32 v17, v17, v8
	v_add_u32_e32 v17, v17, v9
	v_add_u32_e32 v17, v17, v10
	v_add_u32_e32 v17, v17, v11
	v_add_u32_e32 v17, v17, v12
	v_add_u32_e32 v17, v17, v13
	v_add_u32_e32 v17, v17, v14
	v_add_u32_e32 v17, v17, v15
	s_mov_b64 s[4:5], -1
	v_cmp_eq_u32_e32 vcc, s97, v17
	s_cbranch_vccnz .LBB0_79
	s_and_b32 s4, s3, 0xff
	s_cmp_eq_u32 s4, 0
	s_mov_b64 s[4:5], -1
	s_mov_b64 s[14:15], -1
	s_sleep 1
	s_cbranch_scc0 .LBB0_84
	global_load_dword v17, v16, s[70:71] sc1
	s_waitcnt vmcnt(0)
	v_cmp_eq_u32_e32 vcc, 0, v17
	s_cbranch_vccnz .LBB0_86
	s_mov_b64 s[14:15], 0
